# pool phase: counted vmcnt at the compute start (vmcnt(16) for the 15 history rows, vmcnt(15) at the first current row, vmcnt(0) at the end of the first basic block) instead of one vmcnt(0)
# speedup vs baseline: 1.0008x; 1.0008x over previous
.LBB0_986:
	s_waitcnt vmcnt(16)
	v_lshlrev_b32_e32 v129, 16, v59
	v_lshlrev_b32_e32 v128, 16, v58
	v_pk_add_f32 v[128:129], v[128:129], 0 op_sel_hi:[1,0]
	v_lshlrev_b32_e32 v131, 16, v55
	v_lshlrev_b32_e32 v130, 16, v54
	v_pk_fma_f32 v[128:129], v[140:141], v[130:131], v[128:129]
	v_lshlrev_b32_e32 v131, 16, v51
	v_lshlrev_b32_e32 v130, 16, v50
	v_pk_fma_f32 v[128:129], v[140:141], v[130:131], v[128:129]
	v_lshlrev_b32_e32 v173, 16, v47
	v_lshlrev_b32_e32 v172, 16, v46
	v_lshlrev_b32_e32 v181, 16, v43
	v_lshlrev_b32_e32 v180, 16, v42
	v_pk_fma_f32 v[128:129], v[142:143], v[172:173], v[128:129]
	v_lshlrev_b32_e32 v228, 16, v38
	v_lshlrev_b32_e32 v229, 16, v39
	v_pk_fma_f32 v[128:129], v[142:143], v[180:181], v[128:129]
	v_lshlrev_b32_e32 v173, 16, v35
	v_pk_fma_f32 v[128:129], v[142:143], v[228:229], v[128:129]
	v_lshlrev_b32_e32 v172, 16, v34
	v_pk_fma_f32 v[128:129], v[142:143], v[172:173], v[128:129]
	v_lshlrev_b32_e32 v173, 16, v31
	v_lshlrev_b32_e32 v172, 16, v30
	v_pk_fma_f32 v[128:129], v[150:151], v[172:173], v[128:129]
	v_lshlrev_b32_e32 v173, 16, v27
	v_lshlrev_b32_e32 v172, 16, v26
	v_pk_fma_f32 v[128:129], v[150:151], v[172:173], v[128:129]
	v_lshlrev_b32_e32 v173, 16, v23
	v_lshlrev_b32_e32 v172, 16, v22
	v_and_b32_e32 v131, 0xffff0000, v59
	v_and_b32_e32 v130, 0xffff0000, v58
	v_pk_fma_f32 v[128:129], v[150:151], v[172:173], v[128:129]
	v_lshlrev_b32_e32 v173, 16, v19
	v_lshlrev_b32_e32 v172, 16, v18
	v_pk_add_f32 v[130:131], v[130:131], 0 op_sel_hi:[1,0]
	v_and_b32_e32 v133, 0xffff0000, v55
	v_and_b32_e32 v132, 0xffff0000, v54
	v_pk_fma_f32 v[128:129], v[150:151], v[172:173], v[128:129]
	v_lshlrev_b32_e32 v173, 16, v15
	v_lshlrev_b32_e32 v172, 16, v14
	v_pk_fma_f32 v[130:131], v[140:141], v[132:133], v[130:131]
	v_and_b32_e32 v133, 0xffff0000, v51
	v_and_b32_e32 v132, 0xffff0000, v50
	v_pk_fma_f32 v[128:129], v[150:151], v[172:173], v[128:129]
	v_lshlrev_b32_e32 v173, 16, v11
	v_lshlrev_b32_e32 v172, 16, v10
	v_pk_fma_f32 v[130:131], v[140:141], v[132:133], v[130:131]
	v_and_b32_e32 v175, 0xffff0000, v47
	v_and_b32_e32 v174, 0xffff0000, v46
	v_pk_fma_f32 v[128:129], v[150:151], v[172:173], v[128:129]
	v_lshlrev_b32_e32 v173, 16, v5
	v_lshlrev_b32_e32 v172, 16, v4
	v_and_b32_e32 v183, 0xffff0000, v43
	v_and_b32_e32 v182, 0xffff0000, v42
	v_pk_fma_f32 v[172:173], v[150:151], v[172:173], v[128:129]
	v_pk_fma_f32 v[128:129], v[142:143], v[174:175], v[130:131]
	v_and_b32_e32 v230, 0xffff0000, v38
	v_and_b32_e32 v231, 0xffff0000, v39
	v_pk_fma_f32 v[128:129], v[142:143], v[182:183], v[128:129]
	v_and_b32_e32 v131, 0xffff0000, v35
	v_pk_fma_f32 v[128:129], v[142:143], v[230:231], v[128:129]
	v_and_b32_e32 v130, 0xffff0000, v34
	v_pk_fma_f32 v[128:129], v[142:143], v[130:131], v[128:129]
	v_and_b32_e32 v131, 0xffff0000, v31
	v_and_b32_e32 v130, 0xffff0000, v30
	v_pk_fma_f32 v[128:129], v[150:151], v[130:131], v[128:129]
	v_and_b32_e32 v131, 0xffff0000, v27
	v_and_b32_e32 v130, 0xffff0000, v26
	v_pk_fma_f32 v[128:129], v[150:151], v[130:131], v[128:129]
	v_and_b32_e32 v131, 0xffff0000, v23
	v_and_b32_e32 v130, 0xffff0000, v22
	v_lshlrev_b32_e32 v161, 16, v61
	v_lshlrev_b32_e32 v160, 16, v60
	v_pk_fma_f32 v[128:129], v[150:151], v[130:131], v[128:129]
	v_and_b32_e32 v131, 0xffff0000, v19
	v_and_b32_e32 v130, 0xffff0000, v18
	v_pk_add_f32 v[132:133], v[160:161], 0 op_sel_hi:[1,0]
	v_lshlrev_b32_e32 v169, 16, v57
	v_lshlrev_b32_e32 v168, 16, v56
	v_pk_fma_f32 v[128:129], v[150:151], v[130:131], v[128:129]
	v_and_b32_e32 v131, 0xffff0000, v15
	v_and_b32_e32 v130, 0xffff0000, v14
	v_pk_fma_f32 v[132:133], v[140:141], v[168:169], v[132:133]
	v_lshlrev_b32_e32 v135, 16, v53
	v_lshlrev_b32_e32 v134, 16, v52
	v_pk_fma_f32 v[128:129], v[150:151], v[130:131], v[128:129]
	v_and_b32_e32 v131, 0xffff0000, v11
	v_and_b32_e32 v130, 0xffff0000, v10
	v_pk_fma_f32 v[132:133], v[140:141], v[134:135], v[132:133]
	v_lshlrev_b32_e32 v177, 16, v49
	v_lshlrev_b32_e32 v176, 16, v48
	v_pk_fma_f32 v[128:129], v[150:151], v[130:131], v[128:129]
	v_and_b32_e32 v131, 0xffff0000, v5
	v_and_b32_e32 v130, 0xffff0000, v4
	v_lshlrev_b32_e32 v207, 16, v45
	v_lshlrev_b32_e32 v206, 16, v44
	v_pk_fma_f32 v[130:131], v[150:151], v[130:131], v[128:129]
	v_pk_fma_f32 v[128:129], v[142:143], v[176:177], v[132:133]
	v_lshlrev_b32_e32 v232, 16, v40
	v_lshlrev_b32_e32 v233, 16, v41
	v_pk_fma_f32 v[128:129], v[142:143], v[206:207], v[128:129]
	v_lshlrev_b32_e32 v133, 16, v37
	v_pk_fma_f32 v[128:129], v[142:143], v[232:233], v[128:129]
	v_lshlrev_b32_e32 v132, 16, v36
	v_pk_fma_f32 v[128:129], v[142:143], v[132:133], v[128:129]
	v_lshlrev_b32_e32 v133, 16, v33
	v_lshlrev_b32_e32 v132, 16, v32
	v_min_i32_e32 v127, v186, v9
	v_pk_fma_f32 v[128:129], v[150:151], v[132:133], v[128:129]
	v_lshlrev_b32_e32 v133, 16, v29
	v_lshlrev_b32_e32 v132, 16, v28
	v_cndmask_b32_e64 v127, v9, v127, s[68:69]
	v_pk_fma_f32 v[128:129], v[150:151], v[132:133], v[128:129]
	v_lshlrev_b32_e32 v133, 16, v25
	v_lshlrev_b32_e32 v132, 16, v24
	v_cvt_f32_i32_e32 v127, v127
	v_and_b32_e32 v163, 0xffff0000, v61
	v_and_b32_e32 v162, 0xffff0000, v60
	v_pk_fma_f32 v[128:129], v[150:151], v[132:133], v[128:129]
	v_lshlrev_b32_e32 v133, 16, v21
	v_lshlrev_b32_e32 v132, 16, v20
	v_pk_add_f32 v[164:165], v[162:163], 0 op_sel_hi:[1,0]
	v_and_b32_e32 v171, 0xffff0000, v57
	v_and_b32_e32 v170, 0xffff0000, v56
	v_pk_fma_f32 v[128:129], v[150:151], v[132:133], v[128:129]
	v_lshlrev_b32_e32 v133, 16, v17
	v_lshlrev_b32_e32 v132, 16, v16
	v_pk_fma_f32 v[164:165], v[140:141], v[170:171], v[164:165]
	v_and_b32_e32 v167, 0xffff0000, v53
	v_and_b32_e32 v166, 0xffff0000, v52
	v_pk_fma_f32 v[128:129], v[150:151], v[132:133], v[128:129]
	v_lshlrev_b32_e32 v133, 16, v13
	v_lshlrev_b32_e32 v132, 16, v12
	v_pk_fma_f32 v[164:165], v[140:141], v[166:167], v[164:165]
	v_and_b32_e32 v179, 0xffff0000, v49
	v_and_b32_e32 v178, 0xffff0000, v48
	v_pk_fma_f32 v[128:129], v[150:151], v[132:133], v[128:129]
	v_lshlrev_b32_e32 v133, 16, v7
	v_lshlrev_b32_e32 v132, 16, v6
	v_div_scale_f32 v134, s[4:5], v127, v127, 1.0
	v_and_b32_e32 v227, 0xffff0000, v45
	v_and_b32_e32 v226, 0xffff0000, v44
	v_pk_fma_f32 v[174:175], v[150:151], v[132:133], v[128:129]
	v_pk_fma_f32 v[128:129], v[142:143], v[178:179], v[164:165]
	v_rcp_f32_e32 v144, v134
	v_and_b32_e32 v234, 0xffff0000, v40
	v_and_b32_e32 v235, 0xffff0000, v41
	v_pk_fma_f32 v[128:129], v[142:143], v[226:227], v[128:129]
	v_and_b32_e32 v133, 0xffff0000, v37
	v_pk_fma_f32 v[128:129], v[142:143], v[234:235], v[128:129]
	v_and_b32_e32 v132, 0xffff0000, v36
	v_pk_fma_f32 v[128:129], v[142:143], v[132:133], v[128:129]
	v_and_b32_e32 v133, 0xffff0000, v33
	v_and_b32_e32 v132, 0xffff0000, v32
	v_pk_fma_f32 v[128:129], v[150:151], v[132:133], v[128:129]
	v_and_b32_e32 v133, 0xffff0000, v29
	v_and_b32_e32 v132, 0xffff0000, v28
	v_fma_f32 v160, -v134, v144, 1.0
	v_pk_fma_f32 v[128:129], v[150:151], v[132:133], v[128:129]
	v_and_b32_e32 v133, 0xffff0000, v25
	v_and_b32_e32 v132, 0xffff0000, v24
	v_fmac_f32_e32 v144, v160, v144
	v_div_scale_f32 v160, vcc, 1.0, v127, 1.0
	v_pk_fma_f32 v[128:129], v[150:151], v[132:133], v[128:129]
	v_and_b32_e32 v133, 0xffff0000, v21
	v_and_b32_e32 v132, 0xffff0000, v20
	v_mul_f32_e32 v162, v160, v144
	v_pk_fma_f32 v[128:129], v[150:151], v[132:133], v[128:129]
	v_and_b32_e32 v133, 0xffff0000, v17
	v_and_b32_e32 v132, 0xffff0000, v16
	v_fma_f32 v166, -v134, v162, v160
	v_pk_fma_f32 v[128:129], v[150:151], v[132:133], v[128:129]
	v_and_b32_e32 v133, 0xffff0000, v13
	v_and_b32_e32 v132, 0xffff0000, v12
	v_fmac_f32_e32 v162, v166, v144
	v_pk_fma_f32 v[128:129], v[150:151], v[132:133], v[128:129]
	v_and_b32_e32 v133, 0xffff0000, v7
	v_and_b32_e32 v132, 0xffff0000, v6
	v_lshlrev_b32_e32 v207, 16, v3
	v_lshlrev_b32_e32 v206, 16, v2
	v_fma_f32 v134, -v134, v162, v160
	v_pk_fma_f32 v[176:177], v[150:151], v[132:133], v[128:129]
	v_lshlrev_b32_e32 v179, 16, v1
	v_lshlrev_b32_e32 v178, 16, v0
	v_and_b32_e32 v227, 0xffff0000, v3
	v_and_b32_e32 v226, 0xffff0000, v2
	s_waitcnt vmcnt(15)
	v_lshlrev_b32_e32 v164, 16, v64
	v_lshlrev_b32_e32 v165, 16, v65
	v_div_fmas_f32 v134, v134, v144, v162
	v_pk_fma_f32 v[174:175], v[150:151], v[206:207], v[174:175]
	v_and_b32_e32 v183, 0xffff0000, v1
	v_and_b32_e32 v182, 0xffff0000, v0
	v_lshlrev_b32_e32 v180, 16, v62
	v_lshlrev_b32_e32 v181, 16, v63
	v_and_b32_e32 v128, 0xffff0000, v64
	v_and_b32_e32 v129, 0xffff0000, v65
	v_div_fixup_f32 v134, v134, v127, 1.0
	v_pk_fma_f32 v[172:173], v[150:151], v[178:179], v[172:173]
	v_pk_fma_f32 v[176:177], v[150:151], v[226:227], v[176:177]
	v_pk_add_f32 v[174:175], v[174:175], v[164:165]
	v_and_b32_e32 v132, 0xffff0000, v62
	v_and_b32_e32 v133, 0xffff0000, v63
	v_pk_fma_f32 v[130:131], v[150:151], v[182:183], v[130:131]
	v_pk_add_f32 v[178:179], v[172:173], v[180:181]
	v_pk_add_f32 v[176:177], v[176:177], v[128:129]
	v_pk_fma_f32 v[206:207], v[134:135], v[174:175], v[164:165] op_sel_hi:[0,1,1] neg_lo:[0,0,1] neg_hi:[0,0,1]
	v_pk_add_f32 v[172:173], v[130:131], v[132:133]
	v_pk_fma_f32 v[130:131], v[134:135], v[178:179], v[180:181] op_sel_hi:[0,1,1] neg_lo:[0,0,1] neg_hi:[0,0,1]
	v_pk_fma_f32 v[226:227], v[134:135], v[176:177], v[128:129] op_sel_hi:[0,1,1] neg_lo:[0,0,1] neg_hi:[0,0,1]
	v_pk_fma_f32 v[182:183], v[134:135], v[172:173], v[132:133] op_sel_hi:[0,1,1] neg_lo:[0,0,1] neg_hi:[0,0,1]
	v_cvt_pk_bf16_f32 v229, v207, v227
	v_ashrrev_i32_e32 v127, 31, v126
	v_lshlrev_b64 v[126:127], 11, v[126:127]
	v_cvt_pk_bf16_f32 v228, v206, v226
	v_cvt_pk_bf16_f32 v227, v131, v183
	v_cvt_pk_bf16_f32 v226, v130, v182
	v_lshl_add_u64 v[126:127], v[138:139], 0, v[126:127]
	v_add_u32_e32 v144, 0xffffe00f, v158
	global_store_dwordx4 v[126:127], v[226:229], off
	v_lshl_add_u64 v[126:127], s[66:67], 0, v[144:145]
	v_cmp_lt_i32_e32 vcc, s36, v158
	v_lshlrev_b64 v[126:127], 12, v[126:127]
	v_lshl_add_u64 v[126:127], v[154:155], 0, v[126:127]
	s_and_b64 vcc, s[60:61], vcc
	v_subrev_u32_e32 v144, 49, v158
	v_cndmask_b32_e32 v130, 0, v126, vcc
	v_cndmask_b32_e32 v131, 0, v127, vcc
	v_lshl_add_u64 v[126:127], s[66:67], 0, v[144:145]
	v_cmp_lt_i32_e32 vcc, 48, v158
	v_lshlrev_b64 v[126:127], 12, v[126:127]
	v_lshl_add_u64 v[126:127], v[156:157], 0, v[126:127]
	s_and_b64 vcc, s[62:63], vcc
	v_cndmask_b32_e32 v183, v131, v127, vcc
	v_cndmask_b32_e32 v182, v130, v126, vcc
	v_cmp_ne_u64_e32 vcc, 0, v[182:183]
	s_waitcnt vmcnt(0)
	s_and_saveexec_b64 s[4:5], vcc
	s_cbranch_execz .LBB0_988
	v_mov_b32_e32 v130, v180
	v_mov_b32_e32 v131, v132
	v_mov_b32_e32 v132, v181
	v_mov_b32_e32 v126, v164
	v_mov_b32_e32 v127, v128
	v_mov_b32_e32 v128, v165
	global_store_dwordx4 v[182:183], v[130:133], off
	global_store_dwordx4 v[182:183], v[126:129], off offset:16
